# nsa_compress second MLP layer: all 16 weight-tile loads issued together (was 11 serialized load-wait-mfma steps); HGRN off-diagonal slot: no-op clamp removed
# baseline (speedup 1.0000x reference)
; #define LAS __attribute__((address_space(3)))
; DI void hgrn_scan_phase(int wv, const P& p_, LAS unsigned char* lds, float* sumsq) {
;     ...
;   for (int it = blockIdx.x; it < 256; it += gridDim.x) {
;     const int b = it >> 5, hh = (it >> 2) & 7, vq = it & 3;
;     __syncthreads();
;     for (int i = tid; i < 32 * 136 / 2; i += 512) ((LAS unsigned*)ST)[i] = 0u;
;     f32x4 sreg[2]; sreg[0] = (f32x4){0.f, 0.f, 0.f, 0.f}; sreg[1] = sreg[0];
;     u32x4 pq[2], pkk[2], plf[2], pv;
;     const size_t gb = (size_t)(b * SEQ) * 1024 + hh * 128;
.LBB0_430:
	s_mov_b64 s[22:23], 0
	v_readlane_b32 s0, v253, 16
	s_waitcnt vmcnt(4)
	v_mbcnt_lo_u32_b32 v0, -1, 0
	v_mbcnt_hi_u32_b32 v0, -1, v0
	v_readlane_b32 s1, v253, 17
	s_add_i32 s66, s33, -1
	v_add_u32_e32 v0, s69, v0
	s_andn2_b64 vcc, exec, s[0:1]
	s_cbranch_vccnz .LBB0_429
; #define LAS __attribute__((address_space(3)))
; DI unsigned pk2(float a, float b) { typedef __bf16 bf2 __attribute__((ext_vector_type(2))); bf2 v; v[0] = (__bf16)a; v[1] = (__bf16)b; return __builtin_bit_cast(unsigned, v); }
; DI float bf2f(bf16_t v) { return __uint_as_float(((unsigned)v) << 16); }
; #define MFMA16(a, b, c) __builtin_amdgcn_mfma_f32_16x16x32_bf16((a), (b), (c), 0, 0, 0)
; DI void hgrn_scan_phase(int wv, const P& p_, LAS unsigned char* lds, float* sumsq) {
;     ...
;       const int mt = wid >> 1, vt = wid & 1;
;       f32x4 oacc = (f32x4){0.f, 0.f, 0.f, 0.f}, a0 = oacc, a1 = oacc;
;       const int J0 = 2 * vt;
; #pragma unroll
;       for (int ks = 0; ks < 4; ++ks) {
;         const int kb = 32 * ks + 8 * fq, trow = 16 * mt + fr;
;         const bf16x8 qv = *(const LAS bf16x8*)(Q + trow * 136 + kb);
;         const f32x4 bc0 = *(const LAS f32x4*)(BC + trow * 132 + kb), bc1 = *(const LAS f32x4*)(BC + trow * 132 + kb + 4);
;         const f32x4 r0 = *(const LAS f32x4*)(BC + (16 * mt) * 132 + kb), r1 = *(const LAS f32x4*)(BC + (16 * mt) * 132 + kb + 4);
;         u32x4 ai, aq;
; #pragma unroll
;         for (int j = 0; j < 4; ++j) {
;           const float q0 = bf2f((bf16_t)qv[2 * j]), q1 = bf2f((bf16_t)qv[2 * j + 1]);
;           const float b0 = j < 2 ? bc0[2 * j] : bc1[2 * j - 4], b1 = j < 2 ? bc0[2 * j + 1] : bc1[2 * j - 3];
;           const float rr0 = j < 2 ? r0[2 * j] : r1[2 * j - 4], rr1 = j < 2 ? r0[2 * j + 1] : r1[2 * j - 3];
;           ai[j] = pk2(q0 * __builtin_amdgcn_exp2f(b0), q1 * __builtin_amdgcn_exp2f(b1)); aq[j] = pk2(q0 * __builtin_amdgcn_exp2f(b0 - rr0), q1 * __builtin_amdgcn_exp2f(b1 - rr1));
;         }
;         const bf16x8 sb = *(const LAS bf16x8*)(ST + (16 * vt + fr) * 136 + kb);
;         oacc = MFMA16(__builtin_bit_cast(bf16x8, ai), sb, oacc);
; #pragma unroll
;         for (int jj = 0; jj < 2; ++jj) {
;           const int J = J0 + jj; if (J > mt) continue;
;           const int srow = 16 * J + fr;
;     ...
;         for (int reg = 0; reg < 4; ++reg) { const int tt = 16 * mt + 4 * fq + reg, ss = 16 * J + fr; const float v = jj == 0 ? a0[reg] : a1[reg];
;           AB[tt * 72 + ss] = (J <= mt && ss <= tt) ? f2bf(v) : (bf16_t)0; } }
	s_cmp_eq_u32 s66, 0
	s_mov_b32 s0, 0x1f340000
	s_cselect_b32 s0, s0, 0x1f440000
	v_readlane_b32 s1, v255, 32
	s_add_u32 s67, s1, s0
	v_readlane_b32 s0, v255, 34
	v_readlane_b32 s4, v254, 27
	v_add_u32_e32 v4, 0x200, v0
	s_addc_u32 s79, s0, 0
	v_readlane_b32 s6, v254, 29
	v_readlane_b32 s7, v254, 30
	v_readlane_b32 s18, v254, 41
	s_movk_i32 s0, 0x880
	v_lshlrev_b32_e32 v5, 3, v0
	v_ashrrev_i32_e32 v82, 4, v4
	v_ashrrev_i32_e32 v4, 2, v0
	v_readlane_b32 s8, v254, 31
	v_readlane_b32 s9, v254, 32
	v_readlane_b32 s19, v254, 42
	s_add_u32 s24, s18, s22
	v_cmp_gt_i32_e64 s[6:7], s0, v0
	v_and_b32_e32 v78, 0x78, v5
	s_movk_i32 s0, 0x100
	v_and_b32_e32 v6, 24, v5
	v_ashrrev_i32_e32 v5, 31, v4
	v_readlane_b32 s10, v254, 33
	v_readlane_b32 s11, v254, 34
	s_addc_u32 s25, s19, s23
	v_cmp_gt_i32_e64 s[8:9], s0, v0
	s_movk_i32 s0, 0xff
	v_lshlrev_b64 v[8:9], 11, v[4:5]
	v_cmp_lt_i32_e64 s[10:11], s0, v0
	v_lshl_add_u64 v[10:11], s[24:25], 0, v[8:9]
	s_mov_b64 s[0:1], 0xf000000
	v_lshl_add_u64 v[86:87], v[10:11], 0, s[0:1]
	v_readlane_b32 s1, v254, 59
	v_ashrrev_i32_e32 v12, 7, v0
	v_readlane_b32 s5, v254, 28
	v_lshl_add_u32 v7, v4, 1, s1
	v_and_b32_e32 v4, 0x7f, v0
	v_and_b32_e32 v2, 15, v0
	v_lshlrev_b32_e32 v5, 1, v78
	v_readlane_b32 s0, v254, 58
	v_lshlrev_b32_e32 v11, 12, v12
	v_lshlrev_b32_e32 v13, 1, v4
	v_lshlrev_b32_e32 v15, 4, v12
	v_readlane_b32 s4, v254, 61
	v_ashrrev_i32_e32 v3, 6, v0
	s_mov_b32 s98, 0x30201020
	s_mov_b32 s99, 0x21133231
	v_lshlrev_b32_e32 v216, 2, v3
	v_lshrrev_b32_e64 v217, v216, s99
	v_lshrrev_b32_e64 v216, v216, s98
	v_and_b32_e32 v216, 3, v216
	v_and_b32_e32 v217, 3, v217
	v_add_u32_e32 v10, 0, v5
	v_add_u32_e32 v5, s0, v5
	v_add3_u32 v79, s0, v11, v13
	v_readlane_b32 s0, v254, 60
	v_lshlrev_b32_e32 v11, 2, v4
	v_mov_b32_e32 v16, s4
	v_readlane_b32 s5, v254, 62
	v_or_b32_e32 v20, v15, v2
	s_movk_i32 s27, 0x110
	v_bfe_u32 v1, v0, 4, 2
	v_lshlrev_b32_e32 v248, 2, v0
	v_add_u32_e32 v248, 0x1f600, v248
	v_lshlrev_b32_e32 v249, 9, v12
	v_lshl_add_u32 v249, v1, 5, v249
	v_add_u32_e32 v249, 0x1f600, v249
	v_add_u32_e32 v119, s0, v11
	v_add_u32_e32 v120, 0, v11
	v_mad_u32_u24 v16, v4, s90, v16
	v_add_u32_e32 v121, s5, v11
	v_and_b32_e32 v11, 1, v3
	v_mul_lo_u32 v4, v20, s27
	s_add_u32 s28, s24, 0x7000000
	v_add_u32_e32 v21, 0, v4
	v_lshlrev_b32_e32 v22, 8, v20
	v_lshlrev_b32_e32 v4, 4, v11
	v_mul_lo_u32 v20, v20, s90
	v_lshlrev_b32_e32 v26, 4, v1
	v_readlane_b32 s38, v255, 0
	s_addc_u32 s29, s25, 0
	v_or_b32_e32 v23, v4, v2
	v_add3_u32 v123, s38, v20, v26
	v_add_u32_e32 v20, s1, v26
	s_add_u32 s30, s24, 0xb000000
	v_lshlrev_b32_e32 v14, 2, v0
	v_mul_u32_u24_e32 v24, 0x110, v23
	v_mad_u32_u24 v124, v23, s90, v20
	v_and_b32_e32 v23, 0xffffffc0, v0
	s_addc_u32 s31, s25, 0
	v_ashrrev_i32_e32 v76, 4, v0
	v_add_u32_e32 v118, s0, v14
	v_lshlrev_b32_e32 v18, 1, v11
	s_movk_i32 s0, 0x2100
	v_lshl_or_b32 v25, v1, 2, v15
	v_add3_u32 v125, s5, v23, v26
	v_lshl_or_b32 v23, v3, 4, v2
	v_lshl_or_b32 v28, v216, 4, v2
	s_add_u32 s34, s24, 0x17000000
	v_mul_lo_u32 v122, v12, s0
	v_mul_lo_u32 v23, v23, s90
	v_mad_u64_u32 v[88:89], s[0:1], v76, s27, v[10:11]
	v_mad_u64_u32 v[90:91], s[0:1], v82, s27, v[10:11]
	v_cmp_gt_i32_e32 vcc, v216, v12
	v_cmp_gt_i32_e64 s[20:21], v28, v25
	v_or_b32_e32 v10, 1, v25
	s_addc_u32 s35, s25, 0
	v_add3_u32 v126, s4, v23, v26
	s_or_b64 s[4:5], vcc, s[20:21]
	v_cmp_gt_i32_e64 s[20:21], v28, v10
	v_or_b32_e32 v11, 2, v25
	s_or_b64 s[68:69], vcc, s[20:21]
	v_cmp_gt_i32_e64 s[20:21], v28, v11
	v_or_b32_e32 v89, 3, v25
	v_lshl_or_b32 v29, v217, 4, v2
	s_or_b64 s[72:73], vcc, s[20:21]
	v_cmp_gt_i32_e64 s[20:21], v28, v89
	v_readlane_b32 s12, v254, 35
	v_readlane_b32 s13, v254, 36
	v_lshlrev_b32_e32 v19, 3, v1
	v_cmp_gt_i32_e64 s[0:1], v217, v12
	s_or_b64 s[74:75], vcc, s[20:21]
	v_cmp_gt_i32_e32 vcc, v29, v25
	s_movk_i32 s36, 0x90
	s_movk_i32 s26, 0x1100
	v_lshlrev_b32_e32 v1, 5, v1
	v_cmp_gt_u32_e64 s[12:13], s96, v0
	s_or_b64 s[62:63], s[0:1], vcc
	v_cmp_gt_i32_e32 vcc, v29, v10
	v_mul_lo_u32 v30, v12, s26
	v_or_b32_e32 v10, 1, v15
	s_movk_i32 s26, 0x210
	v_add3_u32 v127, v21, v22, v1
	v_add3_u32 v128, 0, v122, v1
	v_mul_lo_u32 v25, v25, s36
	v_lshlrev_b32_e32 v1, 1, v29
	v_add_u32_e32 v134, 0xfffffe00, v0
	v_and_b32_e32 v0, 3, v0
	v_lshl_add_u64 v[8:9], s[22:23], 0, v[8:9]
	v_mul_lo_u32 v15, v10, s26
	v_mul_lo_u32 v31, v10, s27
	v_add3_u32 v130, s38, v25, v1
	v_lshlrev_b32_e32 v0, 4, v0
	v_mov_b32_e32 v1, v32
	v_readlane_b32 s26, v254, 14
	v_lshl_add_u64 v[0:1], v[8:9], 0, v[0:1]
	v_readlane_b32 s27, v254, 15
	v_lshlrev_b32_e32 v3, 5, v3
	v_readlane_b32 s37, v254, 63
	s_or_b64 s[82:83], s[0:1], vcc
	v_cmp_gt_i32_e32 vcc, v29, v11
	v_add_u32_e32 v91, v21, v26
	v_add_u32_e32 v21, 0, v26
	v_lshlrev_b32_e32 v10, 4, v2
	v_mov_b32_e32 v11, v32
	v_lshl_add_u64 v[94:95], s[26:27], 0, v[0:1]
	v_readlane_b32 s26, v252, 14
	v_readlane_b32 s14, v254, 37
	v_readlane_b32 s15, v254, 38
	v_readlane_b32 s16, v254, 39
	v_readlane_b32 s17, v254, 40
	v_ashrrev_i32_e32 v77, 31, v76
	v_ashrrev_i32_e32 v83, 31, v82
	v_sub_u32_e32 v13, v120, v13
	v_lshlrev_b32_e32 v17, 5, v12
	v_add3_u32 v3, s37, v3, v19
	v_lshlrev_b32_e32 v19, 8, v76
	v_lshlrev_b32_e32 v23, 8, v82
	v_mul_u32_u24_e32 v27, 0x90, v6
	s_or_b64 s[90:91], s[0:1], vcc
	v_cmp_gt_i32_e32 vcc, v29, v89
	v_add3_u32 v129, s37, v24, v26
	v_add_u32_e32 v22, v21, v26
	v_lshl_add_u64 v[92:93], s[24:25], 0, v[10:11]
	v_mul_u32_u24_e32 v10, 0x110, v28
	v_mul_u32_u24_e32 v11, 0x210, v28
	v_lshl_add_u32 v24, v28, 1, s38
	v_mul_u32_u24_e32 v26, 0x90, v2
	v_mul_u32_u24_e32 v28, 0x110, v2
	v_readlane_b32 s27, v252, 15
	v_lshlrev_b64 v[80:81], 10, v[76:77]
	v_lshlrev_b64 v[84:85], 10, v[82:83]
	v_cmp_eq_u32_e64 s[14:15], 0, v2
	v_cmp_lt_i32_e64 s[16:17], 0, v12
	v_cmp_lt_i32_e64 s[18:19], 1, v12
	s_or_b64 s[0:1], s[0:1], vcc
	v_cmp_lt_i32_e64 s[20:21], 2, v12
	v_cmp_lt_i32_e64 s[22:23], 3, v12
	v_cmp_le_i32_e64 s[24:25], v216, v12
	v_add_u32_e32 v131, 0x90, v130
	v_add_u32_e32 v132, 0x120, v130
	v_add_u32_e32 v133, 0x1b0, v130
	v_add_u32_e32 v135, s37, v14
	v_lshlrev_b32_e32 v96, 1, v6
	s_waitcnt vmcnt(9)
	v_lshlrev_b32_e32 v98, 1, v4
	v_lshlrev_b32_e32 v100, 1, v2
	v_add_u32_e32 v136, v5, v19
	v_add_u32_e32 v137, v5, v23
	v_add_u32_e32 v138, v7, v27
	v_add_u32_e32 v139, v13, v30
	v_add_u32_e32 v140, v120, v15
	v_add_u32_e32 v141, v13, v31
	v_add_u32_e32 v142, v16, v17
	v_add_u32_e32 v143, v24, v25
	v_add_u32_e32 v144, v20, v26
	v_add_u32_e32 v145, v3, v28
	v_add_u32_e32 v146, v21, v10
	v_add_u32_e32 v147, v22, v11
	v_mul_u32_u24_e32 v218, 0x110, v29
	v_mul_u32_u24_e32 v219, 0x210, v29
	v_add_u32_e32 v218, 0xffffef00, v218
	v_add_u32_e32 v219, 0xffffdf00, v219
	v_add_u32_e32 v218, v21, v218
	v_add_u32_e32 v219, v22, v219
	v_readlane_b32 s54, v254, 12
	s_mov_b32 s57, s26
	v_cmp_le_i32_e64 s[26:27], v217, v12
	s_branch .LBB0_433

; #define LAS __attribute__((address_space(3)))
; DI unsigned pk2(float a, float b) { typedef __bf16 bf2 __attribute__((ext_vector_type(2))); bf2 v; v[0] = (__bf16)a; v[1] = (__bf16)b; return __builtin_bit_cast(unsigned, v); }
; DI float bf2f(bf16_t v) { return __uint_as_float(((unsigned)v) << 16); }
; #define MFMA16(a, b, c) __builtin_amdgcn_mfma_f32_16x16x32_bf16((a), (b), (c), 0, 0, 0)
; DI void hgrn_scan_phase(int wv, const P& p_, LAS unsigned char* lds, float* sumsq) {
;     ...
;         for (int jj = 0; jj < 2; ++jj) {
;           const int J = J0 + jj; if (J > mt) continue;
;           const int srow = 16 * J + fr;
;           const bf16x8 kv = *(const LAS bf16x8*)(Kr + srow * 136 + kb);
;           const f32x4 c0 = *(const LAS f32x4*)(BC + srow * 132 + kb), c1 = *(const LAS f32x4*)(BC + srow * 132 + kb + 4);
;           u32x4 bk;
; #pragma unroll
;           for (int j = 0; j < 4; ++j) {
;             const float k0 = bf2f((bf16_t)kv[2 * j]), k1 = bf2f((bf16_t)kv[2 * j + 1]);
;             const float b0 = j < 2 ? c0[2 * j] : c1[2 * j - 4], b1 = j < 2 ? c0[2 * j + 1] : c1[2 * j - 3];
;             const float rr0 = j < 2 ? r0[2 * j] : r1[2 * j - 4], rr1 = j < 2 ? r0[2 * j + 1] : r1[2 * j - 3];
;             bk[j] = pk2(k0 * __builtin_amdgcn_exp2f(fminf(rr0 - b0, 115.f)), k1 * __builtin_amdgcn_exp2f(fminf(rr1 - b1, 115.f)));
;           }
;           if (jj == 0) a0 = MFMA16(__builtin_bit_cast(bf16x8, aq), __builtin_bit_cast(bf16x8, bk), a0);
;           else a1 = MFMA16(__builtin_bit_cast(bf16x8, aq), __builtin_bit_cast(bf16x8, bk), a1);
.LBB0_452:
	s_or_b64 exec, exec, vcc
	v_mov_b64_e32 v[46:47], v[34:35]
	v_mov_b64_e32 v[44:45], v[32:33]
	s_and_saveexec_b64 vcc, s[26:27]
	s_cbranch_execz .LBB0_454
	ds_read_b128 v[44:47], v219 offset:43264
	ds_read_b128 v[148:151], v218 offset:21760
	ds_read_b128 v[152:155], v219 offset:43280
	s_waitcnt lgkmcnt(2)
	v_sub_f32_e32 v33, v64, v44
	v_sub_f32_e32 v34, v65, v45
	v_mov_b32_e32 v35, v34
	v_exp_f32_e32 v34, v33
	v_sub_f32_e32 v33, v66, v46
	v_exp_f32_e32 v35, v35
	v_exp_f32_e32 v46, v33
	v_sub_f32_e32 v33, v67, v47
	v_exp_f32_e32 v47, v33
	s_waitcnt lgkmcnt(1)
	v_and_b32_e32 v45, 0xffff0000, v148
	v_lshlrev_b32_e32 v44, 16, v148
	v_pk_mul_f32 v[34:35], v[34:35], v[44:45]
	s_waitcnt lgkmcnt(0)
	v_sub_f32_e32 v33, v56, v152
	v_cvt_pk_bf16_f32 v44, v34, v35
	v_and_b32_e32 v35, 0xffff0000, v149
	v_lshlrev_b32_e32 v34, 16, v149
	v_pk_mul_f32 v[34:35], v[46:47], v[34:35]
	v_exp_f32_e32 v46, v33
	v_sub_f32_e32 v33, v57, v153
	v_exp_f32_e32 v47, v33
	v_sub_f32_e32 v33, v58, v154
	v_exp_f32_e32 v56, v33
	v_sub_f32_e32 v33, v59, v155
	v_exp_f32_e32 v57, v33
	v_cvt_pk_bf16_f32 v45, v34, v35
	v_and_b32_e32 v35, 0xffff0000, v150
	v_lshlrev_b32_e32 v34, 16, v150
	v_pk_mul_f32 v[34:35], v[46:47], v[34:35]
	s_nop 0
	v_cvt_pk_bf16_f32 v46, v34, v35
	v_and_b32_e32 v35, 0xffff0000, v151
	v_lshlrev_b32_e32 v34, 16, v151
	v_pk_mul_f32 v[34:35], v[56:57], v[34:35]
	s_nop 0
	v_cvt_pk_bf16_f32 v47, v34, v35
	s_nop 1
	v_mfma_f32_16x16x32_bf16 v[44:47], v[60:63], v[44:47], 0

; #define LAS __attribute__((address_space(3)))
; DI unsigned pk2(float a, float b) { typedef __bf16 bf2 __attribute__((ext_vector_type(2))); bf2 v; v[0] = (__bf16)a; v[1] = (__bf16)b; return __builtin_bit_cast(unsigned, v); }
; DI float bf2f(bf16_t v) { return __uint_as_float(((unsigned)v) << 16); }
; #define MFMA16(a, b, c) __builtin_amdgcn_mfma_f32_16x16x32_bf16((a), (b), (c), 0, 0, 0)
; DI void hgrn_scan_phase(int wv, const P& p_, LAS unsigned char* lds, float* sumsq) {
;     ...
;         for (int jj = 0; jj < 2; ++jj) {
;           const int J = J0 + jj; if (J > mt) continue;
;           const int srow = 16 * J + fr;
;           const bf16x8 kv = *(const LAS bf16x8*)(Kr + srow * 136 + kb);
;           const f32x4 c0 = *(const LAS f32x4*)(BC + srow * 132 + kb), c1 = *(const LAS f32x4*)(BC + srow * 132 + kb + 4);
;           u32x4 bk;
; #pragma unroll
;           for (int j = 0; j < 4; ++j) {
;             const float k0 = bf2f((bf16_t)kv[2 * j]), k1 = bf2f((bf16_t)kv[2 * j + 1]);
;             const float b0 = j < 2 ? c0[2 * j] : c1[2 * j - 4], b1 = j < 2 ? c0[2 * j + 1] : c1[2 * j - 3];
;             const float rr0 = j < 2 ? r0[2 * j] : r1[2 * j - 4], rr1 = j < 2 ? r0[2 * j + 1] : r1[2 * j - 3];
;             bk[j] = pk2(k0 * __builtin_amdgcn_exp2f(fminf(rr0 - b0, 115.f)), k1 * __builtin_amdgcn_exp2f(fminf(rr1 - b1, 115.f)));
;           }
;           if (jj == 0) a0 = MFMA16(__builtin_bit_cast(bf16x8, aq), __builtin_bit_cast(bf16x8, bk), a0);
;           else a1 = MFMA16(__builtin_bit_cast(bf16x8, aq), __builtin_bit_cast(bf16x8, bk), a1);
.LBB0_456:
	s_or_b64 exec, exec, vcc
	s_and_saveexec_b64 vcc, s[26:27]
	s_cbranch_execz .LBB0_458
	ds_read_b128 v[148:151], v219 offset:43392
	ds_read_b128 v[152:155], v218 offset:21824
	ds_read_b128 v[156:159], v219 offset:43408
	s_waitcnt lgkmcnt(2)
	v_sub_f32_e32 v33, v68, v148
	v_sub_f32_e32 v68, v69, v149
	v_mov_b32_e32 v69, v68
	v_exp_f32_e32 v68, v33
	v_sub_f32_e32 v33, v70, v150
	v_exp_f32_e32 v70, v33
	v_sub_f32_e32 v33, v71, v151
	v_exp_f32_e32 v71, v33
	s_waitcnt lgkmcnt(0)
	v_sub_f32_e32 v33, v60, v156
	v_exp_f32_e32 v60, v33
	v_sub_f32_e32 v33, v61, v157
	v_exp_f32_e32 v69, v69
	v_exp_f32_e32 v61, v33
	v_sub_f32_e32 v33, v62, v158
	v_and_b32_e32 v149, 0xffff0000, v152
	v_lshlrev_b32_e32 v148, 16, v152
	v_exp_f32_e32 v62, v33
	v_sub_f32_e32 v33, v63, v159
	v_pk_mul_f32 v[68:69], v[68:69], v[148:149]
	v_and_b32_e32 v149, 0xffff0000, v153
	v_lshlrev_b32_e32 v148, 16, v153
	v_pk_mul_f32 v[70:71], v[70:71], v[148:149]
	v_exp_f32_e32 v63, v33
	v_cvt_pk_bf16_f32 v68, v68, v69
	v_cvt_pk_bf16_f32 v69, v70, v71
	v_and_b32_e32 v71, 0xffff0000, v154
	v_lshlrev_b32_e32 v70, 16, v154
	v_pk_mul_f32 v[60:61], v[60:61], v[70:71]
	s_nop 0
	v_cvt_pk_bf16_f32 v70, v60, v61
	v_and_b32_e32 v61, 0xffff0000, v155
	v_lshlrev_b32_e32 v60, 16, v155
	v_pk_mul_f32 v[60:61], v[62:63], v[60:61]
	s_nop 0
	v_cvt_pk_bf16_f32 v71, v60, v61
	s_nop 1
	v_mfma_f32_16x16x32_bf16 v[44:47], v[64:67], v[68:71], v[44:47]

; #define LAS __attribute__((address_space(3)))
; DI unsigned pk2(float a, float b) { typedef __bf16 bf2 __attribute__((ext_vector_type(2))); bf2 v; v[0] = (__bf16)a; v[1] = (__bf16)b; return __builtin_bit_cast(unsigned, v); }
; DI float bf2f(bf16_t v) { return __uint_as_float(((unsigned)v) << 16); }
; #define MFMA16(a, b, c) __builtin_amdgcn_mfma_f32_16x16x32_bf16((a), (b), (c), 0, 0, 0)
; DI void hgrn_scan_phase(int wv, const P& p_, LAS unsigned char* lds, float* sumsq) {
;     ...
;         for (int jj = 0; jj < 2; ++jj) {
;           const int J = J0 + jj; if (J > mt) continue;
;           const int srow = 16 * J + fr;
;           const bf16x8 kv = *(const LAS bf16x8*)(Kr + srow * 136 + kb);
;           const f32x4 c0 = *(const LAS f32x4*)(BC + srow * 132 + kb), c1 = *(const LAS f32x4*)(BC + srow * 132 + kb + 4);
;           u32x4 bk;
; #pragma unroll
;           for (int j = 0; j < 4; ++j) {
;             const float k0 = bf2f((bf16_t)kv[2 * j]), k1 = bf2f((bf16_t)kv[2 * j + 1]);
;             const float b0 = j < 2 ? c0[2 * j] : c1[2 * j - 4], b1 = j < 2 ? c0[2 * j + 1] : c1[2 * j - 3];
;             const float rr0 = j < 2 ? r0[2 * j] : r1[2 * j - 4], rr1 = j < 2 ? r0[2 * j + 1] : r1[2 * j - 3];
;             bk[j] = pk2(k0 * __builtin_amdgcn_exp2f(fminf(rr0 - b0, 115.f)), k1 * __builtin_amdgcn_exp2f(fminf(rr1 - b1, 115.f)));
;           }
;           if (jj == 0) a0 = MFMA16(__builtin_bit_cast(bf16x8, aq), __builtin_bit_cast(bf16x8, bk), a0);
;           else a1 = MFMA16(__builtin_bit_cast(bf16x8, aq), __builtin_bit_cast(bf16x8, bk), a1);
.LBB0_460:
	s_or_b64 exec, exec, vcc
	s_and_saveexec_b64 vcc, s[26:27]
	s_cbranch_execz .LBB0_462
	ds_read_b128 v[148:151], v219 offset:43520
	ds_read_b128 v[152:155], v218 offset:21888
	ds_read_b128 v[156:159], v219 offset:43536
	s_waitcnt lgkmcnt(2)
	v_sub_f32_e32 v33, v68, v148
	v_sub_f32_e32 v68, v69, v149
	v_mov_b32_e32 v69, v68
	v_exp_f32_e32 v68, v33
	v_sub_f32_e32 v33, v70, v150
	v_exp_f32_e32 v70, v33
	v_sub_f32_e32 v33, v71, v151
	v_exp_f32_e32 v71, v33
	s_waitcnt lgkmcnt(0)
	v_sub_f32_e32 v33, v60, v156
	v_exp_f32_e32 v60, v33
	v_sub_f32_e32 v33, v61, v157
	v_exp_f32_e32 v69, v69
	v_exp_f32_e32 v61, v33
	v_sub_f32_e32 v33, v62, v158
	v_and_b32_e32 v149, 0xffff0000, v152
	v_lshlrev_b32_e32 v148, 16, v152
	v_exp_f32_e32 v62, v33
	v_sub_f32_e32 v33, v63, v159
	v_pk_mul_f32 v[68:69], v[68:69], v[148:149]
	v_and_b32_e32 v149, 0xffff0000, v153
	v_lshlrev_b32_e32 v148, 16, v153
	v_pk_mul_f32 v[70:71], v[70:71], v[148:149]
	v_exp_f32_e32 v63, v33
	v_cvt_pk_bf16_f32 v68, v68, v69
	v_cvt_pk_bf16_f32 v69, v70, v71
	v_and_b32_e32 v71, 0xffff0000, v154
	v_lshlrev_b32_e32 v70, 16, v154
	v_pk_mul_f32 v[60:61], v[60:61], v[70:71]
	s_nop 0
	v_cvt_pk_bf16_f32 v70, v60, v61
	v_and_b32_e32 v61, 0xffff0000, v155
	v_lshlrev_b32_e32 v60, 16, v155
	v_pk_mul_f32 v[60:61], v[62:63], v[60:61]
	s_nop 0
	v_cvt_pk_bf16_f32 v71, v60, v61
	s_nop 1
	v_mfma_f32_16x16x32_bf16 v[44:47], v[64:67], v[68:71], v[44:47]

; #define LAS __attribute__((address_space(3)))
; DI unsigned pk2(float a, float b) { typedef __bf16 bf2 __attribute__((ext_vector_type(2))); bf2 v; v[0] = (__bf16)a; v[1] = (__bf16)b; return __builtin_bit_cast(unsigned, v); }
; DI float bf2f(bf16_t v) { return __uint_as_float(((unsigned)v) << 16); }
; #define MFMA16(a, b, c) __builtin_amdgcn_mfma_f32_16x16x32_bf16((a), (b), (c), 0, 0, 0)
; DI void hgrn_scan_phase(int wv, const P& p_, LAS unsigned char* lds, float* sumsq) {
;     ...
;         for (int jj = 0; jj < 2; ++jj) {
;           const int J = J0 + jj; if (J > mt) continue;
;           const int srow = 16 * J + fr;
;           const bf16x8 kv = *(const LAS bf16x8*)(Kr + srow * 136 + kb);
;           const f32x4 c0 = *(const LAS f32x4*)(BC + srow * 132 + kb), c1 = *(const LAS f32x4*)(BC + srow * 132 + kb + 4);
;           u32x4 bk;
; #pragma unroll
;           for (int j = 0; j < 4; ++j) {
;             const float k0 = bf2f((bf16_t)kv[2 * j]), k1 = bf2f((bf16_t)kv[2 * j + 1]);
;             const float b0 = j < 2 ? c0[2 * j] : c1[2 * j - 4], b1 = j < 2 ? c0[2 * j + 1] : c1[2 * j - 3];
;             const float rr0 = j < 2 ? r0[2 * j] : r1[2 * j - 4], rr1 = j < 2 ? r0[2 * j + 1] : r1[2 * j - 3];
;             bk[j] = pk2(k0 * __builtin_amdgcn_exp2f(fminf(rr0 - b0, 115.f)), k1 * __builtin_amdgcn_exp2f(fminf(rr1 - b1, 115.f)));
;           }
;           if (jj == 0) a0 = MFMA16(__builtin_bit_cast(bf16x8, aq), __builtin_bit_cast(bf16x8, bk), a0);
;           else a1 = MFMA16(__builtin_bit_cast(bf16x8, aq), __builtin_bit_cast(bf16x8, bk), a1);
.LBB0_464:
	s_or_b64 exec, exec, vcc
	s_and_saveexec_b64 vcc, s[26:27]
	s_cbranch_execz .LBB0_466
	ds_read_b128 v[148:151], v219 offset:43648
	ds_read_b128 v[152:155], v218 offset:21952
	ds_read_b128 v[156:159], v219 offset:43664
	s_waitcnt lgkmcnt(2)
	v_sub_f32_e32 v33, v68, v148
	v_sub_f32_e32 v68, v69, v149
	v_mov_b32_e32 v69, v68
	v_exp_f32_e32 v68, v33
	v_sub_f32_e32 v33, v70, v150
	v_exp_f32_e32 v70, v33
	v_sub_f32_e32 v33, v71, v151
	v_exp_f32_e32 v71, v33
	s_waitcnt lgkmcnt(0)
	v_sub_f32_e32 v33, v60, v156
	v_exp_f32_e32 v60, v33
	v_sub_f32_e32 v33, v61, v157
	v_exp_f32_e32 v69, v69
	v_exp_f32_e32 v61, v33
	v_sub_f32_e32 v33, v62, v158
	v_and_b32_e32 v149, 0xffff0000, v152
	v_lshlrev_b32_e32 v148, 16, v152
	v_exp_f32_e32 v62, v33
	v_sub_f32_e32 v33, v63, v159
	v_pk_mul_f32 v[68:69], v[68:69], v[148:149]
	v_and_b32_e32 v149, 0xffff0000, v153
	v_lshlrev_b32_e32 v148, 16, v153
	v_pk_mul_f32 v[70:71], v[70:71], v[148:149]
	v_exp_f32_e32 v63, v33
	v_cvt_pk_bf16_f32 v68, v68, v69
	v_cvt_pk_bf16_f32 v69, v70, v71
	v_and_b32_e32 v71, 0xffff0000, v154
	v_lshlrev_b32_e32 v70, 16, v154
	v_pk_mul_f32 v[60:61], v[60:61], v[70:71]
	s_nop 0
	v_cvt_pk_bf16_f32 v70, v60, v61
	v_and_b32_e32 v61, 0xffff0000, v155
	v_lshlrev_b32_e32 v60, 16, v155
	v_pk_mul_f32 v[60:61], v[62:63], v[60:61]
	s_nop 0
	v_cvt_pk_bf16_f32 v71, v60, v61
	s_nop 1
	v_mfma_f32_16x16x32_bf16 v[44:47], v[64:67], v[68:71], v[44:47]

; #define LAS __attribute__((address_space(3)))
; #define MFMA16(a, b, c) __builtin_amdgcn_mfma_f32_16x16x32_bf16((a), (b), (c), 0, 0, 0)
; DI void nsa_compress_phase(int wv, const P& p_, LAS unsigned char* lds) {
;     ...
;     if (!half) {
;       f32x4 o[4];
; #pragma unroll
;       for (int i = 0; i < 4; ++i) o[i] = (f32x4){0.f, 0.f, 0.f, 0.f};
; #pragma unroll
;       for (int ks = 0; ks < 4; ++ks) { const bf16x8 af = *(const LAS bf16x8*)(hid + fr * 136 + ks * 32 + fq * 8);
; #pragma unroll
;         for (int nt = 0; nt < 4; ++nt) { const bf16x8 bfr = *(const bf16x8*)(w2t + (size_t)(nt * 16 + fr) * 128 + ks * 32 + fq * 8); o[nt] = MFMA16(af, bfr, o[nt]); } }
;       bf16_t* dst = (bf16_t*)(p.ws + (kv ? WS_VC : WS_KC)) + (size_t)((b * 4 + g) * 256) * 64;
; #pragma unroll
;       for (int nt = 0; nt < 4; ++nt)
; #pragma unroll
;         for (int j = 0; j < 4; ++j) { const int nn = n0 + 4 * fq + j; dst[(size_t)nn * 64 + nt * 16 + fr] = nn > 254 ? (bf16_t)0 : f2bf(o[nt][j]); }
;     }
.LBB0_544:
	s_and_b64 vcc, exec, s[6:7]
	s_waitcnt lgkmcnt(0)
	s_barrier
	s_cbranch_vccnz .LBB0_534
	s_lshl_b64 s[6:7], s[10:11], 14
	v_lshl_add_u64 v[34:35], v[74:75], 0, s[6:7]
	v_mov_b32_e32 v81, v32
	v_mov_b32_e32 v83, v32
	v_mov_b32_e32 v85, v32
	v_mov_b32_e32 v87, v32
	v_lshl_add_u64 v[36:37], v[34:35], 0, v[80:81]
	v_lshl_add_u64 v[16:17], v[34:35], 0, v[82:83]
	v_lshl_add_u64 v[20:21], v[34:35], 0, v[84:85]
	v_lshl_add_u64 v[24:25], v[34:35], 0, v[86:87]
	global_load_dwordx4 v[110:113], v[36:37], off
	global_load_dwordx4 v[114:117], v[16:17], off
	global_load_dwordx4 v[118:121], v[20:21], off
	global_load_dwordx4 v[122:125], v[24:25], off
	global_load_dwordx4 v[126:129], v[36:37], off offset:64
	global_load_dwordx4 v[130:133], v[16:17], off offset:64
	global_load_dwordx4 v[134:137], v[20:21], off offset:64
	global_load_dwordx4 v[138:141], v[24:25], off offset:64
	global_load_dwordx4 v[142:145], v[36:37], off offset:128
	global_load_dwordx4 v[146:149], v[16:17], off offset:128
	global_load_dwordx4 v[150:153], v[20:21], off offset:128
	global_load_dwordx4 v[154:157], v[24:25], off offset:128
	global_load_dwordx4 v[158:161], v[36:37], off offset:192
	global_load_dwordx4 v[162:165], v[16:17], off offset:192
	global_load_dwordx4 v[166:169], v[20:21], off offset:192
	global_load_dwordx4 v[170:173], v[24:25], off offset:192
	ds_read_b128 v[174:177], v94
	ds_read_b128 v[178:181], v94 offset:64
	ds_read_b128 v[182:185], v94 offset:128
	ds_read_b128 v[186:189], v94 offset:192
	s_mov_b64 s[6:7], 0xc0
	s_cmpk_lt_u32 s15, 0x200
	s_mov_b32 s6, 0x1f540000
	s_cselect_b32 s6, 0x1f440000, s6
	s_add_u32 s6, s0, s6
	s_addc_u32 s7, s1, 0
	s_lshl_b32 s10, s17, 15
	s_lshl_b32 s11, s18, 17
	s_or_b32 s10, s11, s10
	s_add_u32 s6, s6, s10
	s_addc_u32 s7, s7, 0
	s_movk_i32 s10, 0xfc
	s_waitcnt vmcnt(0) lgkmcnt(0)
	v_mfma_f32_16x16x32_bf16 v[28:31], v[174:177], v[110:113], 0
	v_mfma_f32_16x16x32_bf16 v[16:19], v[174:177], v[114:117], 0
	v_mfma_f32_16x16x32_bf16 v[12:15], v[174:177], v[118:121], 0
	v_mfma_f32_16x16x32_bf16 v[8:11], v[174:177], v[122:125], 0
	v_mfma_f32_16x16x32_bf16 v[28:31], v[178:181], v[126:129], v[28:31]
	v_mfma_f32_16x16x32_bf16 v[16:19], v[178:181], v[130:133], v[16:19]
	v_mfma_f32_16x16x32_bf16 v[12:15], v[178:181], v[134:137], v[12:15]
	v_mfma_f32_16x16x32_bf16 v[8:11], v[178:181], v[138:141], v[8:11]
	v_mfma_f32_16x16x32_bf16 v[28:31], v[182:185], v[142:145], v[28:31]
	v_mfma_f32_16x16x32_bf16 v[16:19], v[182:185], v[146:149], v[16:19]
	v_mfma_f32_16x16x32_bf16 v[12:15], v[182:185], v[150:153], v[12:15]
	v_mfma_f32_16x16x32_bf16 v[8:11], v[182:185], v[154:157], v[8:11]
	v_mfma_f32_16x16x32_bf16 v[28:31], v[186:189], v[158:161], v[28:31]
	v_mfma_f32_16x16x32_bf16 v[16:19], v[186:189], v[162:165], v[16:19]
	v_mfma_f32_16x16x32_bf16 v[12:15], v[186:189], v[166:169], v[12:15]
	v_mfma_f32_16x16x32_bf16 v[8:11], v[186:189], v[170:173], v[8:11]
	s_nop 7
	s_nop 7
	v_cvt_pk_bf16_f32 v16, v16, s0
	v_cvt_pk_bf16_f32 v12, v12, s0
	v_or_b32_e32 v20, s16, v71
	v_lshlrev_b32_e32 v22, 6, v20
	v_or_b32_e32 v23, v22, v33
	v_cvt_pk_bf16_f32 v21, v28, s0
	v_lshlrev_b32_e32 v23, 1, v23
	global_store_short v23, v21, s[6:7]
	v_cvt_pk_bf16_f32 v21, v29, s0
	v_cmp_eq_u32_e32 vcc, s10, v20
	v_cvt_pk_bf16_f32 v20, v31, s0
	global_store_short v23, v16, s[6:7] offset:32
	v_cvt_pk_bf16_f32 v16, v17, s0
	v_or_b32_e32 v17, v22, v97
	global_store_short v23, v21, s[6:7] offset:128
	v_cvt_pk_bf16_f32 v21, v30, s0
	v_cndmask_b32_e64 v20, v20, 0, vcc
	v_lshlrev_b32_e32 v17, 1, v17
	global_store_short v23, v21, s[6:7] offset:256
	global_store_short v23, v20, s[6:7] offset:384
	global_store_short v17, v16, s[6:7] offset:128
	v_cvt_pk_bf16_f32 v16, v18, s0
	global_store_short v17, v16, s[6:7] offset:256
	v_cvt_pk_bf16_f32 v16, v19, s0
	v_cndmask_b32_e64 v16, v16, 0, vcc
	global_store_short v17, v16, s[6:7] offset:384
	global_store_short v23, v12, s[6:7] offset:64
	v_cvt_pk_bf16_f32 v12, v13, s0
	v_or_b32_e32 v13, v22, v98
	v_lshlrev_b32_e32 v13, 1, v13
	global_store_short v13, v12, s[6:7] offset:128
	v_cvt_pk_bf16_f32 v12, v14, s0
	global_store_short v13, v12, s[6:7] offset:256
	v_cvt_pk_bf16_f32 v12, v15, s0
	v_cndmask_b32_e64 v12, v12, 0, vcc
	v_cvt_pk_bf16_f32 v8, v8, s0
	global_store_short v13, v12, s[6:7] offset:384
	global_store_short v23, v8, s[6:7] offset:96
	v_cvt_pk_bf16_f32 v8, v9, s0
	v_or_b32_e32 v9, v22, v99
	v_lshlrev_b32_e32 v9, 1, v9
	global_store_short v9, v8, s[6:7] offset:128
	v_cvt_pk_bf16_f32 v8, v10, s0
	global_store_short v9, v8, s[6:7] offset:256
	v_cvt_pk_bf16_f32 v8, v11, s0
	v_cndmask_b32_e64 v8, v8, 0, vcc
	global_store_short v9, v8, s[6:7] offset:384
	s_branch .LBB0_534
